# v89 plus in-projection vT path: lanes transposed with ds_bpermute so each quad stores 64 contiguous bytes of one feature row
# speedup vs baseline: 1.0060x; 1.0060x over previous
.LBB0_431:
	s_andn2_b64 vcc, exec, s[4:5]
	s_cbranch_vccnz .LBB0_391
	v_or_b32_e32 v0, s7, v199
	s_lshl_b32 s7, s35, 8
	s_cmp_lt_u32 s35, 30
	s_mov_b64 s[4:5], -1
	v_ashrrev_i32_e32 v1, 31, v0
	s_cbranch_scc1 .LBB0_434
	s_waitcnt lgkmcnt(0)
	v_readlane_b32 s4, v252, 15
	v_readlane_b32 s5, v252, 16
	v_and_b32_e32 v2, 3, v220
	v_and_b32_e32 v0, 0xffffffe0, v0
	v_lshl_or_b32 v0, v2, 3, v0
	v_ashrrev_i32_e32 v1, 31, v0
	v_add_u32_e32 v10, s7, v200
	v_and_b32_e32 v8, 15, v220
	v_sub_u32_e32 v10, v10, v8
	v_bfe_u32 v8, v220, 2, 4
	v_add_u32_e32 v10, v10, v8
	v_lshl_or_b32 v9, v2, 4, v8
	v_lshlrev_b32_e32 v9, 2, v9
	v_lshlrev_b64 v[6:7], 1, v[0:1]
	v_mov_b64_e32 v[2:3], s[4:5]
	v_mad_i64_i32 v[4:5], s[4:5], v10, s94, v[2:3]
	v_lshl_add_u64 v[4:5], v[4:5], 0, v[6:7]
	v_cvt_pk_f16_f32 v158, v158, v159
	v_cvt_pk_f16_f32 v159, v160, v161
	v_cvt_pk_f16_f32 v160, v142, v143
	v_cvt_pk_f16_f32 v161, v144, v145
	v_cvt_pk_f16_f32 v94, v94, v95
	v_cvt_pk_f16_f32 v95, v96, v97
	v_cvt_pk_f16_f32 v96, v78, v79
	v_cvt_pk_f16_f32 v97, v80, v81
	v_permlane32_swap_b32_e32 v158, v160
	v_permlane32_swap_b32_e32 v159, v161
	v_permlane32_swap_b32_e32 v94, v96
	v_permlane32_swap_b32_e32 v95, v97
	v_permlane16_swap_b32_e32 v158, v160
	v_permlane16_swap_b32_e32 v159, v161
	v_permlane16_swap_b32_e32 v94, v96
	v_permlane16_swap_b32_e32 v95, v97
	s_nop 1
	ds_bpermute_b32 v158, v9, v158
	ds_bpermute_b32 v159, v9, v159
	ds_bpermute_b32 v160, v9, v160
	ds_bpermute_b32 v161, v9, v161
	ds_bpermute_b32 v94, v9, v94
	ds_bpermute_b32 v95, v9, v95
	ds_bpermute_b32 v96, v9, v96
	ds_bpermute_b32 v97, v9, v97
	s_waitcnt lgkmcnt(0)
	global_store_dwordx4 v[4:5], v[158:161], off
	global_store_dwordx4 v[4:5], v[94:97], off offset:256
	s_nop 1
	v_or_b32_e32 v4, 16, v10
	v_mad_i64_i32 v[4:5], s[4:5], v4, s94, v[2:3]
	v_lshl_add_u64 v[4:5], v[4:5], 0, v[6:7]
	v_cvt_pk_f16_f32 v150, v150, v151
	v_cvt_pk_f16_f32 v151, v152, v153
	v_cvt_pk_f16_f32 v152, v134, v135
	v_cvt_pk_f16_f32 v153, v136, v137
	v_cvt_pk_f16_f32 v86, v86, v87
	v_cvt_pk_f16_f32 v87, v88, v89
	v_cvt_pk_f16_f32 v88, v70, v71
	v_cvt_pk_f16_f32 v89, v72, v73
	v_permlane32_swap_b32_e32 v150, v152
	v_permlane32_swap_b32_e32 v151, v153
	v_permlane32_swap_b32_e32 v86, v88
	v_permlane32_swap_b32_e32 v87, v89
	v_permlane16_swap_b32_e32 v150, v152
	v_permlane16_swap_b32_e32 v151, v153
	v_permlane16_swap_b32_e32 v86, v88
	v_permlane16_swap_b32_e32 v87, v89
	s_nop 1
	ds_bpermute_b32 v150, v9, v150
	ds_bpermute_b32 v151, v9, v151
	ds_bpermute_b32 v152, v9, v152
	ds_bpermute_b32 v153, v9, v153
	ds_bpermute_b32 v86, v9, v86
	ds_bpermute_b32 v87, v9, v87
	ds_bpermute_b32 v88, v9, v88
	ds_bpermute_b32 v89, v9, v89
	s_waitcnt lgkmcnt(0)
	global_store_dwordx4 v[4:5], v[150:153], off
	global_store_dwordx4 v[4:5], v[86:89], off offset:256
	s_nop 1
	v_or_b32_e32 v4, 32, v10
	v_mad_i64_i32 v[4:5], s[4:5], v4, s94, v[2:3]
	v_lshl_add_u64 v[4:5], v[4:5], 0, v[6:7]
	v_cvt_pk_f16_f32 v154, v154, v155
	v_cvt_pk_f16_f32 v155, v156, v157
	v_cvt_pk_f16_f32 v156, v138, v139
	v_cvt_pk_f16_f32 v157, v140, v141
	v_cvt_pk_f16_f32 v90, v90, v91
	v_cvt_pk_f16_f32 v91, v92, v93
	v_cvt_pk_f16_f32 v92, v74, v75
	v_cvt_pk_f16_f32 v93, v76, v77
	v_permlane32_swap_b32_e32 v154, v156
	v_permlane32_swap_b32_e32 v155, v157
	v_permlane32_swap_b32_e32 v90, v92
	v_permlane32_swap_b32_e32 v91, v93
	v_permlane16_swap_b32_e32 v154, v156
	v_permlane16_swap_b32_e32 v155, v157
	v_permlane16_swap_b32_e32 v90, v92
	v_permlane16_swap_b32_e32 v91, v93
	s_nop 1
	ds_bpermute_b32 v154, v9, v154
	ds_bpermute_b32 v155, v9, v155
	ds_bpermute_b32 v156, v9, v156
	ds_bpermute_b32 v157, v9, v157
	ds_bpermute_b32 v90, v9, v90
	ds_bpermute_b32 v91, v9, v91
	ds_bpermute_b32 v92, v9, v92
	ds_bpermute_b32 v93, v9, v93
	s_waitcnt lgkmcnt(0)
	global_store_dwordx4 v[4:5], v[154:157], off
	global_store_dwordx4 v[4:5], v[90:93], off offset:256
	s_nop 1
	v_or_b32_e32 v4, 48, v10
	v_mad_i64_i32 v[4:5], s[4:5], v4, s94, v[2:3]
	v_lshl_add_u64 v[4:5], v[4:5], 0, v[6:7]
	v_cvt_pk_f16_f32 v146, v146, v147
	v_cvt_pk_f16_f32 v147, v148, v149
	v_cvt_pk_f16_f32 v148, v130, v131
	v_cvt_pk_f16_f32 v149, v132, v133
	v_cvt_pk_f16_f32 v82, v82, v83
	v_cvt_pk_f16_f32 v83, v84, v85
	v_cvt_pk_f16_f32 v84, v66, v67
	v_cvt_pk_f16_f32 v85, v68, v69
	v_permlane32_swap_b32_e32 v146, v148
	v_permlane32_swap_b32_e32 v147, v149
	v_permlane32_swap_b32_e32 v82, v84
	v_permlane32_swap_b32_e32 v83, v85
	v_permlane16_swap_b32_e32 v146, v148
	v_permlane16_swap_b32_e32 v147, v149
	v_permlane16_swap_b32_e32 v82, v84
	v_permlane16_swap_b32_e32 v83, v85
	s_nop 1
	ds_bpermute_b32 v146, v9, v146
	ds_bpermute_b32 v147, v9, v147
	ds_bpermute_b32 v148, v9, v148
	ds_bpermute_b32 v149, v9, v149
	ds_bpermute_b32 v82, v9, v82
	ds_bpermute_b32 v83, v9, v83
	ds_bpermute_b32 v84, v9, v84
	ds_bpermute_b32 v85, v9, v85
	s_waitcnt lgkmcnt(0)
	global_store_dwordx4 v[4:5], v[146:149], off
	global_store_dwordx4 v[4:5], v[82:85], off offset:256
	s_nop 1
	v_add_u32_e32 v4, 0x80, v10
	v_mad_i64_i32 v[4:5], s[4:5], v4, s94, v[2:3]
	v_lshl_add_u64 v[4:5], v[4:5], 0, v[6:7]
	v_cvt_pk_f16_f32 v126, v126, v127
	v_cvt_pk_f16_f32 v127, v128, v129
	v_cvt_pk_f16_f32 v128, v110, v111
	v_cvt_pk_f16_f32 v129, v112, v113
	v_cvt_pk_f16_f32 v62, v62, v63
	v_cvt_pk_f16_f32 v63, v64, v65
	v_cvt_pk_f16_f32 v64, v46, v47
	v_cvt_pk_f16_f32 v65, v48, v49
	v_permlane32_swap_b32_e32 v126, v128
	v_permlane32_swap_b32_e32 v127, v129
	v_permlane32_swap_b32_e32 v62, v64
	v_permlane32_swap_b32_e32 v63, v65
	v_permlane16_swap_b32_e32 v126, v128
	v_permlane16_swap_b32_e32 v127, v129
	v_permlane16_swap_b32_e32 v62, v64
	v_permlane16_swap_b32_e32 v63, v65
	s_nop 1
	ds_bpermute_b32 v126, v9, v126
	ds_bpermute_b32 v127, v9, v127
	ds_bpermute_b32 v128, v9, v128
	ds_bpermute_b32 v129, v9, v129
	ds_bpermute_b32 v62, v9, v62
	ds_bpermute_b32 v63, v9, v63
	ds_bpermute_b32 v64, v9, v64
	ds_bpermute_b32 v65, v9, v65
	s_waitcnt lgkmcnt(0)
	global_store_dwordx4 v[4:5], v[126:129], off
	global_store_dwordx4 v[4:5], v[62:65], off offset:256
	s_nop 1
	v_add_u32_e32 v4, 0x90, v10
	v_mad_i64_i32 v[4:5], s[4:5], v4, s94, v[2:3]
	v_lshl_add_u64 v[4:5], v[4:5], 0, v[6:7]
	v_cvt_pk_f16_f32 v118, v118, v119
	v_cvt_pk_f16_f32 v119, v120, v121
	v_cvt_pk_f16_f32 v120, v102, v103
	v_cvt_pk_f16_f32 v121, v104, v105
	v_cvt_pk_f16_f32 v54, v54, v55
	v_cvt_pk_f16_f32 v55, v56, v57
	v_cvt_pk_f16_f32 v56, v38, v39
	v_cvt_pk_f16_f32 v57, v40, v41
	v_permlane32_swap_b32_e32 v118, v120
	v_permlane32_swap_b32_e32 v119, v121
	v_permlane32_swap_b32_e32 v54, v56
	v_permlane32_swap_b32_e32 v55, v57
	v_permlane16_swap_b32_e32 v118, v120
	v_permlane16_swap_b32_e32 v119, v121
	v_permlane16_swap_b32_e32 v54, v56
	v_permlane16_swap_b32_e32 v55, v57
	s_nop 1
	ds_bpermute_b32 v118, v9, v118
	ds_bpermute_b32 v119, v9, v119
	ds_bpermute_b32 v120, v9, v120
	ds_bpermute_b32 v121, v9, v121
	ds_bpermute_b32 v54, v9, v54
	ds_bpermute_b32 v55, v9, v55
	ds_bpermute_b32 v56, v9, v56
	ds_bpermute_b32 v57, v9, v57
	s_waitcnt lgkmcnt(0)
	global_store_dwordx4 v[4:5], v[118:121], off
	global_store_dwordx4 v[4:5], v[54:57], off offset:256
	s_nop 1
	v_add_u32_e32 v4, 0xa0, v10
	v_mad_i64_i32 v[4:5], s[4:5], v4, s94, v[2:3]
	v_lshl_add_u64 v[4:5], v[4:5], 0, v[6:7]
	v_cvt_pk_f16_f32 v122, v122, v123
	v_cvt_pk_f16_f32 v123, v124, v125
	v_cvt_pk_f16_f32 v124, v106, v107
	v_cvt_pk_f16_f32 v125, v108, v109
	v_cvt_pk_f16_f32 v58, v58, v59
	v_cvt_pk_f16_f32 v59, v60, v61
	v_cvt_pk_f16_f32 v60, v42, v43
	v_cvt_pk_f16_f32 v61, v44, v45
	v_permlane32_swap_b32_e32 v122, v124
	v_permlane32_swap_b32_e32 v123, v125
	v_permlane32_swap_b32_e32 v58, v60
	v_permlane32_swap_b32_e32 v59, v61
	v_permlane16_swap_b32_e32 v122, v124
	v_permlane16_swap_b32_e32 v123, v125
	v_permlane16_swap_b32_e32 v58, v60
	v_permlane16_swap_b32_e32 v59, v61
	s_nop 1
	ds_bpermute_b32 v122, v9, v122
	ds_bpermute_b32 v123, v9, v123
	ds_bpermute_b32 v124, v9, v124
	ds_bpermute_b32 v125, v9, v125
	ds_bpermute_b32 v58, v9, v58
	ds_bpermute_b32 v59, v9, v59
	ds_bpermute_b32 v60, v9, v60
	ds_bpermute_b32 v61, v9, v61
	s_waitcnt lgkmcnt(0)
	global_store_dwordx4 v[4:5], v[122:125], off
	global_store_dwordx4 v[4:5], v[58:61], off offset:256
	s_nop 1
	v_add_u32_e32 v4, 0xb0, v10
	v_mad_i64_i32 v[4:5], s[4:5], v4, s94, v[2:3]
	v_lshl_add_u64 v[4:5], v[4:5], 0, v[6:7]
	v_cvt_pk_f16_f32 v114, v114, v115
	v_cvt_pk_f16_f32 v115, v116, v117
	v_cvt_pk_f16_f32 v116, v98, v99
	v_cvt_pk_f16_f32 v117, v100, v101
	v_cvt_pk_f16_f32 v50, v50, v51
	v_cvt_pk_f16_f32 v51, v52, v53
	v_cvt_pk_f16_f32 v52, v34, v35
	v_cvt_pk_f16_f32 v53, v36, v37
	v_permlane32_swap_b32_e32 v114, v116
	v_permlane32_swap_b32_e32 v115, v117
	v_permlane32_swap_b32_e32 v50, v52
	v_permlane32_swap_b32_e32 v51, v53
	v_permlane16_swap_b32_e32 v114, v116
	v_permlane16_swap_b32_e32 v115, v117
	v_permlane16_swap_b32_e32 v50, v52
	v_permlane16_swap_b32_e32 v51, v53
	s_nop 1
	ds_bpermute_b32 v114, v9, v114
	ds_bpermute_b32 v115, v9, v115
	ds_bpermute_b32 v116, v9, v116
	ds_bpermute_b32 v117, v9, v117
	ds_bpermute_b32 v50, v9, v50
	ds_bpermute_b32 v51, v9, v51
	ds_bpermute_b32 v52, v9, v52
	ds_bpermute_b32 v53, v9, v53
	s_waitcnt lgkmcnt(0)
	global_store_dwordx4 v[4:5], v[114:117], off
	global_store_dwordx4 v[4:5], v[50:53], off offset:256
	s_nop 1
	s_mov_b64 s[4:5], 0
